# speedup vs baseline: 1.0082x; 1.0035x over previous
; __device__ __forceinline__ float fexp2(float x) { return __builtin_amdgcn_exp2f(x); }
; template <int MODE>
; __device__ __forceinline__ void sb_step(const char* Kb, const char* Vb, const bf16x8 (&qf)[2][2], const SbConst& U,
;                                         f32x4 (&oacc)[4][2], float (&carry)[2], int key0, int q0, int fr, int fq) {
;     ...
; #pragma unroll
;   for (int ks = 0; ks < 2; ++ks)
; #pragma unroll
;     for (int m = 0; m < 4; ++m) {
;       if (SB_CLS(m, 0) > 0 && SB_CLS(m, 1) > 0) continue;
;       const bf16x8 kf = *(const bf16x8*)(Kb + (m * 16 + fr) * 144 + ks * 64 + fq * 16);
; #pragma unroll
;       for (int n = 0; n < 2; ++n)
;         if (SB_CLS(m, n) <= 0) s[m][n] = mfma16(kf, qf[n][ks], s[m][n]);
;     }
; #pragma unroll
;   for (int n = 0; n < 2; ++n) {
;     unsigned pk[8];
;     const int tq = q0 + n * 16 + fr;
; #pragma unroll
;     for (int m = 0; m < 4; ++m) {
;       if (SB_CLS(m, n) > 0) { pk[m * 2] = 0u; pk[m * 2 + 1] = 0u; continue; }
;       float spv[4];
; #pragma unroll
;       for (int r = 0; r < 4; ++r) {
;         const float z = fminf(s[m][n][r], 80.f);
;         const float e = fexp2(z);
;         float sp = flog2(1.0f + e);
;         float ls = z - sp;
;         if (SB_CLS(m, n) == 0) {
;           const int key = key0 + m * 16 + fq * 4 + r;
;           if (key >= tq) { sp = 0.f; ls = -1e30f; }
;         }
;         spv[r] = sp;
;         s[m][n][r] = ls;
;       }
;       pk[m * 2] = pack2(spv[0], spv[1]);
;       pk[m * 2 + 1] = pack2(spv[2], spv[3]);
;     }
;     const bf16x8 sp0 = mk8(pk[0], pk[1], pk[2], pk[3]);
;     const bf16x8 sp1 = mk8(pk[4], pk[5], pk[6], pk[7]);
;     const float c = carry[n];
;     const f32x4 cin = {c, c, c, c};
;     const f32x4 X1 = mfma16(U.U_ONES, sp1, cin);
;     const f32x4 I0 = mfma16(U.U_TRI1, sp0, X1);
;     const f32x4 I1 = mfma16(U.U_0TRI, sp0, X1);
;     const f32x4 TOT = mfma16(U.U_ONES, sp0, X1);
;     const f32x4 I2 = mfma16(U.U_TRI1, sp1, cin);
;     const f32x4 I3 = mfma16(U.U_0TRI, sp1, cin);
; #pragma unroll
;     for (int r = 0; r < 4; ++r) {
;       s[0][n][r] = (SB_CLS(0, n) > 0) ? 0.f : fexp2(s[0][n][r] - I0[r]);
;       s[1][n][r] = (SB_CLS(1, n) > 0) ? 0.f : fexp2(s[1][n][r] - I1[r]);
;       s[2][n][r] = (SB_CLS(2, n) > 0) ? 0.f : fexp2(s[2][n][r] - I2[r]);
;       s[3][n][r] = (SB_CLS(3, n) > 0) ? 0.f : fexp2(s[3][n][r] - I3[r]);
;     }
.LBB0_393:
	v_cmp_le_i32_e64 s[10:11], s25, v156
	s_xor_b64 s[12:13], s[70:71], -1
	s_and_b64 s[10:11], s[10:11], s[12:13]
	s_andn2_b64 s[12:13], s[70:71], exec
	s_and_b64 s[14:15], s[70:71], exec
	s_or_b64 s[70:71], s[12:13], s[14:15]
	s_and_saveexec_b64 s[74:75], s[10:11]
	s_cbranch_execz .LBB0_392
	v_cmp_ne_u32_e64 s[10:11], s94, v192
	s_and_saveexec_b64 s[12:13], s[10:11]
	s_xor_b64 s[54:55], exec, s[12:13]
	s_cbranch_execz .LBB0_400
	s_waitcnt lgkmcnt(3)
	ds_read_b128 v[136:139], v159
	s_waitcnt lgkmcnt(3)
	ds_read_b128 v[132:135], v159 offset:2304
	s_waitcnt lgkmcnt(3)
	ds_read_b128 v[128:131], v159 offset:4608
	s_waitcnt lgkmcnt(3)
	ds_read_b128 v[124:127], v159 offset:6912
	v_cmp_ne_u32_e64 s[10:11], s94, v191
	s_and_saveexec_b64 s[12:13], s[10:11]
	s_xor_b64 s[10:11], exec, s[12:13]
	s_cbranch_execz .LBB0_397
	ds_read_b128 v[180:183], v159 offset:64
	s_waitcnt lgkmcnt(4)
	v_mfma_f32_16x16x32_bf16 v[140:143], v[136:139], v[68:71], 0
	s_mov_b32 s58, s56
	s_mov_b32 s59, s56
	s_mov_b32 s57, s56
	v_mfma_f32_16x16x32_bf16 v[136:139], v[136:139], v[76:79], 0
	s_waitcnt lgkmcnt(0)
	v_mfma_f32_16x16x32_bf16 v[194:197], v[180:183], v[72:75], v[140:143]
	s_nop 2
	ds_read_b128 v[140:143], v159 offset:2368
	v_mfma_f32_16x16x32_bf16 v[144:147], v[132:135], v[68:71], 0
	s_nop 2
	v_min_f32_e32 v86, 0x42a00000, v196
	v_exp_f32_e32 v87, v86
	v_mfma_f32_16x16x32_bf16 v[132:135], v[132:135], v[76:79], 0
	v_add_f32_e32 v87, 1.0, v87
	v_log_f32_e32 v87, v87
	v_mfma_f32_16x16x32_bf16 v[136:139], v[180:183], v[80:83], v[136:139]
	v_min_f32_e32 v0, 0x42a00000, v194
	v_min_f32_e32 v3, 0x42a00000, v195
	v_sub_f32_e32 v97, v86, v87
	v_min_f32_e32 v86, 0x42a00000, v197
	v_exp_f32_e32 v98, v86
	s_waitcnt lgkmcnt(0)
	v_mfma_f32_16x16x32_bf16 v[180:183], v[140:143], v[72:75], v[144:147]
	v_exp_f32_e32 v1, v0
	v_exp_f32_e32 v85, v3
	v_add_f32_e32 v98, 1.0, v98
	v_mfma_f32_16x16x32_bf16 v[132:135], v[140:143], v[80:83], v[132:135]
	ds_read_b128 v[140:143], v159 offset:4672
	ds_read_b128 v[144:147], v159 offset:6976
	v_log_f32_e32 v98, v98
	v_mfma_f32_16x16x32_bf16 v[148:151], v[128:131], v[68:71], 0
	v_add_f32_e32 v1, 1.0, v1
	v_add_f32_e32 v85, 1.0, v85
	v_sub_f32_e32 v99, v86, v98
	v_mfma_f32_16x16x32_bf16 v[128:131], v[128:131], v[76:79], 0
	v_min_f32_e32 v86, 0x42a00000, v181
	v_log_f32_e32 v1, v1
	v_mfma_f32_16x16x32_bf16 v[152:155], v[124:127], v[68:71], 0
	v_log_f32_e32 v85, v85
	v_sub_f32_e32 v0, v0, v1
	v_mfma_f32_16x16x32_bf16 v[124:127], v[124:127], v[76:79], 0
	v_sub_f32_e32 v3, v3, v85
	s_waitcnt lgkmcnt(1)
	v_mfma_f32_16x16x32_bf16 v[148:151], v[140:143], v[72:75], v[148:151]
	v_mfma_f32_16x16x32_bf16 v[128:131], v[140:143], v[80:83], v[128:131]
	s_waitcnt lgkmcnt(0)
	v_mfma_f32_16x16x32_bf16 v[140:143], v[144:147], v[72:75], v[152:155]
	v_mfma_f32_16x16x32_bf16 v[124:127], v[144:147], v[80:83], v[124:127]
	v_cvt_pk_bf16_f32 v145, v87, v98
	v_exp_f32_e32 v87, v86
	v_cvt_pk_bf16_f32 v144, v1, v85
	v_min_f32_e32 v1, 0x42a00000, v180
	v_add_f32_e32 v87, 1.0, v87
	v_log_f32_e32 v87, v87
	v_exp_f32_e32 v85, v1
	v_sub_f32_e32 v98, v86, v87
	v_min_f32_e32 v86, 0x42a00000, v182
	v_exp_f32_e32 v146, v86
	v_add_f32_e32 v85, 1.0, v85
	v_log_f32_e32 v85, v85
	v_add_f32_e32 v146, 1.0, v146
	v_log_f32_e32 v147, v146
	v_sub_f32_e32 v1, v1, v85
	v_sub_f32_e32 v193, v86, v147
	v_min_f32_e32 v86, 0x42a00000, v183
	v_exp_f32_e32 v146, v86
	s_nop 0
	v_add_f32_e32 v146, 1.0, v146
	v_log_f32_e32 v152, v146
	v_cvt_pk_bf16_f32 v146, v85, v87
	v_min_f32_e32 v85, 0x42a00000, v148
	v_sub_f32_e32 v202, v86, v152
	v_exp_f32_e32 v86, v85
	v_cvt_pk_bf16_f32 v147, v147, v152
	v_add_f32_e32 v86, 1.0, v86
	v_log_f32_e32 v86, v86
	s_nop 0
	v_sub_f32_e32 v203, v85, v86
	v_min_f32_e32 v85, 0x42a00000, v149
	v_exp_f32_e32 v87, v85
	s_nop 0
	v_add_f32_e32 v87, 1.0, v87
	v_log_f32_e32 v87, v87
	s_nop 0
	v_sub_f32_e32 v204, v85, v87
	v_min_f32_e32 v85, 0x42a00000, v150
	v_exp_f32_e32 v148, v85
	s_nop 0
	v_add_f32_e32 v148, 1.0, v148
	v_log_f32_e32 v149, v148
	s_nop 0
	v_sub_f32_e32 v205, v85, v149
	v_min_f32_e32 v85, 0x42a00000, v151
	v_exp_f32_e32 v148, v85
	s_nop 0
	v_add_f32_e32 v148, 1.0, v148
	v_log_f32_e32 v150, v148
	v_cvt_pk_bf16_f32 v148, v86, v87
	v_sub_f32_e32 v206, v85, v150
	v_min_f32_e32 v85, 0x42a00000, v140
	v_exp_f32_e32 v86, v85
	v_cvt_pk_bf16_f32 v149, v149, v150
	v_add_f32_e32 v86, 1.0, v86
	v_log_f32_e32 v86, v86
	s_nop 0
	v_sub_f32_e32 v207, v85, v86
	v_min_f32_e32 v85, 0x42a00000, v141
	v_exp_f32_e32 v87, v85
	s_nop 0
	v_add_f32_e32 v87, 1.0, v87
	v_log_f32_e32 v87, v87
	s_nop 0
	v_sub_f32_e32 v208, v85, v87
	v_min_f32_e32 v85, 0x42a00000, v142
	v_exp_f32_e32 v140, v85
	v_cvt_pk_bf16_f32 v150, v86, v87
	v_mov_b32_e32 v86, v84
	v_mov_b32_e32 v87, v84
	v_add_f32_e32 v140, 1.0, v140
	v_log_f32_e32 v140, v140
	s_nop 0
	v_sub_f32_e32 v209, v85, v140
	v_min_f32_e32 v85, 0x42a00000, v143
	v_exp_f32_e32 v141, v85
	s_nop 0
	v_add_f32_e32 v141, 1.0, v141
	v_log_f32_e32 v141, v141
	s_nop 0
	v_sub_f32_e32 v210, v85, v141
	v_cvt_pk_bf16_f32 v151, v140, v141
	v_mov_b64_e32 v[142:143], s[58:59]
	v_mov_b64_e32 v[140:141], s[56:57]
	v_mov_b32_e32 v85, v84
	s_nop 1
	v_mfma_f32_16x16x32_bf16 v[180:183], v[140:143], v[148:151], v[84:87]
	v_mfma_f32_16x16x32_bf16 v[152:155], v[4:7], v[144:147], v[180:183]
	v_mfma_f32_16x16x32_bf16 v[194:197], v[64:67], v[144:147], v[180:183]
	v_mfma_f32_16x16x32_bf16 v[198:201], v[4:7], v[148:151], v[84:87]
	s_nop 5
	v_sub_f32_e32 v0, v0, v152
	v_exp_f32_e32 v211, v0
	v_sub_f32_e32 v0, v1, v194
	v_mfma_f32_16x16x32_bf16 v[84:87], v[64:67], v[148:151], v[84:87]
	v_sub_f32_e32 v3, v3, v153
	v_exp_f32_e32 v153, v3
	v_sub_f32_e32 v3, v98, v195
; template <int MODE>
; __device__ __forceinline__ void sb_step(const char* Kb, const char* Vb, const bf16x8 (&qf)[2][2], const SbConst& U,
;                                         f32x4 (&oacc)[4][2], float (&carry)[2], int key0, int q0, int fr, int fq) {
;     ...
;   for (int n = 0; n < 2; ++n) {
;     unsigned pk[8];
;     const int tq = q0 + n * 16 + fr;
; #pragma unroll
;     for (int m = 0; m < 4; ++m) {
;       if (SB_CLS(m, n) > 0) { pk[m * 2] = 0u; pk[m * 2 + 1] = 0u; continue; }
;       float spv[4];
; #pragma unroll
;       for (int r = 0; r < 4; ++r) {
;         const float z = fminf(s[m][n][r], 80.f);
;         const float e = fexp2(z);
;         float sp = flog2(1.0f + e);
;         float ls = z - sp;
;         if (SB_CLS(m, n) == 0) {
;           const int key = key0 + m * 16 + fq * 4 + r;
;           if (key >= tq) { sp = 0.f; ls = -1e30f; }
;         }
;         spv[r] = sp;
;         s[m][n][r] = ls;
;       }
;       pk[m * 2] = pack2(spv[0], spv[1]);
;       pk[m * 2 + 1] = pack2(spv[2], spv[3]);
;     }
;     const bf16x8 sp0 = mk8(pk[0], pk[1], pk[2], pk[3]);
;     const bf16x8 sp1 = mk8(pk[4], pk[5], pk[6], pk[7]);
;     const float c = carry[n];
;     const f32x4 cin = {c, c, c, c};
;     const f32x4 X1 = mfma16(U.U_ONES, sp1, cin);
;     const f32x4 I0 = mfma16(U.U_TRI1, sp0, X1);
;     const f32x4 I1 = mfma16(U.U_0TRI, sp0, X1);
;     const f32x4 TOT = mfma16(U.U_ONES, sp0, X1);
;     const f32x4 I2 = mfma16(U.U_TRI1, sp1, cin);
;     const f32x4 I3 = mfma16(U.U_0TRI, sp1, cin);
; #pragma unroll
;     for (int r = 0; r < 4; ++r) {
;       s[0][n][r] = (SB_CLS(0, n) > 0) ? 0.f : fexp2(s[0][n][r] - I0[r]);
;       s[1][n][r] = (SB_CLS(1, n) > 0) ? 0.f : fexp2(s[1][n][r] - I1[r]);
;       s[2][n][r] = (SB_CLS(2, n) > 0) ? 0.f : fexp2(s[2][n][r] - I2[r]);
;       s[3][n][r] = (SB_CLS(3, n) > 0) ? 0.f : fexp2(s[3][n][r] - I3[r]);
;     }
;     carry[n] = TOT[0];
;   }
;     ...
; #pragma unroll
;   for (int ks = 0; ks < 2; ++ks) {
;     bf16x8 pf[2];
; #pragma unroll
;     for (int n = 0; n < 2; ++n)
;       pf[n] = mk8(pack2(s[2 * ks][n][0], s[2 * ks][n][1]), pack2(s[2 * ks][n][2], s[2 * ks][n][3]),
;                   pack2(s[2 * ks + 1][n][0], s[2 * ks + 1][n][1]), pack2(s[2 * ks + 1][n][2], s[2 * ks + 1][n][3]));
; #pragma unroll
;     for (int mt = 0; mt < 4; ++mt) {
;       const char* vp = Vb + (mt * 16 + fr) * 144 + (32 * ks + 4 * fq) * 2;
	v_max_f32_e32 v98, v138, v138
	v_min_f32_e32 v98, 0x42a00000, v98
	s_nop 2
	v_sub_f32_e32 v1, v207, v84
	v_sub_f32_e32 v84, v208, v85
	v_exp_f32_e32 v148, v84
	v_sub_f32_e32 v84, v97, v154
	v_exp_f32_e32 v154, v84
	v_sub_f32_e32 v84, v193, v196
	v_exp_f32_e32 v193, v84
	v_sub_f32_e32 v84, v205, v200
	v_exp_f32_e32 v149, v84
	v_sub_f32_e32 v84, v209, v86
	v_exp_f32_e32 v150, v84
	v_sub_f32_e32 v84, v99, v155
	v_exp_f32_e32 v99, v98
	v_exp_f32_e32 v155, v84
	v_sub_f32_e32 v84, v202, v197
	v_exp_f32_e32 v196, v84
	v_add_f32_e32 v99, 1.0, v99
	v_log_f32_e32 v99, v99
	v_sub_f32_e32 v84, v206, v201
	v_exp_f32_e32 v151, v84
	v_sub_f32_e32 v84, v210, v87
	v_sub_f32_e32 v197, v98, v99
	v_exp_f32_e32 v152, v84
	v_mfma_f32_16x16x32_bf16 v[84:87], v[140:143], v[144:147], v[180:183]
	v_min_f32_e32 v98, 0x42a00000, v139
	v_exp_f32_e32 v194, v0
	v_sub_f32_e32 v0, v203, v198
	v_exp_f32_e32 v195, v3
	v_sub_f32_e32 v3, v204, v199
	s_nop 2
	v_max_f32_e32 v85, v136, v136
	v_exp_f32_e32 v136, v98
	v_min_f32_e32 v85, 0x42a00000, v85
	v_min_f32_e32 v87, 0x42a00000, v137
	v_add_f32_e32 v136, 1.0, v136
	v_log_f32_e32 v137, v136
	v_exp_f32_e32 v86, v85
	v_exp_f32_e32 v97, v87
	v_exp_f32_e32 v0, v0
	v_sub_f32_e32 v198, v98, v137
	v_min_f32_e32 v98, 0x42a00000, v133
	v_cvt_pk_bf16_f32 v137, v99, v137
	v_exp_f32_e32 v99, v98
	v_add_f32_e32 v86, 1.0, v86
	v_add_f32_e32 v97, 1.0, v97
	v_log_f32_e32 v86, v86
	v_add_f32_e32 v99, 1.0, v99
	v_log_f32_e32 v99, v99
	v_log_f32_e32 v97, v97
	v_sub_f32_e32 v85, v85, v86
	v_exp_f32_e32 v1, v1
	v_sub_f32_e32 v199, v98, v99
	v_min_f32_e32 v98, 0x42a00000, v134
	v_cvt_pk_bf16_f32 v136, v86, v97
	v_max_f32_e32 v86, v132, v132
	v_exp_f32_e32 v132, v98
	v_min_f32_e32 v86, 0x42a00000, v86
	v_sub_f32_e32 v87, v87, v97
	v_exp_f32_e32 v97, v86
	v_add_f32_e32 v132, 1.0, v132
	v_log_f32_e32 v132, v132
	v_exp_f32_e32 v3, v3
	v_add_f32_e32 v97, 1.0, v97
	v_log_f32_e32 v97, v97
	v_sub_f32_e32 v200, v98, v132
	v_min_f32_e32 v98, 0x42a00000, v135
	v_exp_f32_e32 v133, v98
	v_sub_f32_e32 v86, v86, v97
	v_cvt_pk_bf16_f32 v138, v97, v99
	v_add_f32_e32 v133, 1.0, v133
	v_log_f32_e32 v133, v133
	v_min_f32_e32 v97, 0x42a00000, v128
	v_sub_f32_e32 v201, v98, v133
	v_exp_f32_e32 v98, v97
	v_cvt_pk_bf16_f32 v139, v132, v133
	v_add_f32_e32 v98, 1.0, v98
	v_log_f32_e32 v98, v98
	s_nop 0
	v_sub_f32_e32 v202, v97, v98
	v_min_f32_e32 v97, 0x42a00000, v129
	v_exp_f32_e32 v99, v97
	s_nop 0
	v_add_f32_e32 v99, 1.0, v99
	v_log_f32_e32 v99, v99
	s_nop 0
	v_sub_f32_e32 v203, v97, v99
	v_min_f32_e32 v97, 0x42a00000, v130
	v_exp_f32_e32 v128, v97
	s_nop 0
	v_add_f32_e32 v128, 1.0, v128
	v_log_f32_e32 v129, v128
	s_nop 0
	v_sub_f32_e32 v204, v97, v129
	v_min_f32_e32 v97, 0x42a00000, v131
	v_exp_f32_e32 v128, v97
	s_nop 0
	v_add_f32_e32 v128, 1.0, v128
	v_log_f32_e32 v130, v128
	v_cvt_pk_bf16_f32 v128, v98, v99
	v_sub_f32_e32 v205, v97, v130
	v_min_f32_e32 v97, 0x42a00000, v124
	v_exp_f32_e32 v98, v97
	v_cvt_pk_bf16_f32 v129, v129, v130
	v_add_f32_e32 v98, 1.0, v98
	v_log_f32_e32 v98, v98
	s_nop 0
	v_sub_f32_e32 v206, v97, v98
	v_min_f32_e32 v97, 0x42a00000, v125
	v_exp_f32_e32 v99, v97
	s_nop 0
	v_add_f32_e32 v99, 1.0, v99
	v_log_f32_e32 v99, v99
	s_nop 0
	v_sub_f32_e32 v207, v97, v99
	v_min_f32_e32 v97, 0x42a00000, v126
	v_exp_f32_e32 v124, v97
	v_cvt_pk_bf16_f32 v130, v98, v99
	v_mov_b32_e32 v98, v96
	v_mov_b32_e32 v99, v96
	v_add_f32_e32 v124, 1.0, v124
	v_log_f32_e32 v124, v124
	s_nop 0
	v_sub_f32_e32 v208, v97, v124
	v_min_f32_e32 v97, 0x42a00000, v127
	v_exp_f32_e32 v125, v97
	s_nop 0
	v_add_f32_e32 v125, 1.0, v125
	v_log_f32_e32 v125, v125
	s_nop 0
	v_sub_f32_e32 v209, v97, v125
	v_cvt_pk_bf16_f32 v131, v124, v125
	v_mov_b32_e32 v97, v96
	s_nop 1
	v_mfma_f32_16x16x32_bf16 v[124:127], v[140:143], v[128:131], v[96:99]
	v_mfma_f32_16x16x32_bf16 v[180:183], v[4:7], v[128:131], v[96:99]
	v_mfma_f32_16x16x32_bf16 v[96:99], v[64:67], v[128:131], v[96:99]
	v_mfma_f32_16x16x32_bf16 v[144:147], v[64:67], v[136:139], v[124:127]
	s_nop 5
	v_sub_f32_e32 v128, v202, v180
	v_sub_f32_e32 v96, v206, v96
	v_exp_f32_e32 v180, v96
	v_mfma_f32_16x16x32_bf16 v[132:135], v[4:7], v[136:139], v[124:127]
	v_sub_f32_e32 v96, v199, v145
	v_exp_f32_e32 v130, v96
	v_sub_f32_e32 v96, v203, v181
	v_exp_f32_e32 v145, v96
	v_sub_f32_e32 v96, v207, v97
	v_exp_f32_e32 v181, v96
	s_nop 1
	v_sub_f32_e32 v96, v197, v134
	v_exp_f32_e32 v129, v96
	v_sub_f32_e32 v96, v200, v146
	v_exp_f32_e32 v131, v96
	v_sub_f32_e32 v96, v204, v182
	v_exp_f32_e32 v146, v96
	v_sub_f32_e32 v96, v208, v98
	v_exp_f32_e32 v182, v96
	v_sub_f32_e32 v96, v198, v135
	v_sub_f32_e32 v85, v85, v132
	v_exp_f32_e32 v132, v96
	v_sub_f32_e32 v96, v201, v147
	v_sub_f32_e32 v87, v87, v133
	v_exp_f32_e32 v133, v96
	v_cvt_pk_bf16_f32 v129, v129, v132
	v_sub_f32_e32 v86, v86, v144
	v_exp_f32_e32 v85, v85
	v_cvt_pk_bf16_f32 v131, v131, v133
	ds_read2_b64 v[132:135], v177 offset1:4
	v_exp_f32_e32 v86, v86
	v_exp_f32_e32 v87, v87
	v_sub_f32_e32 v96, v205, v183
	v_exp_f32_e32 v147, v96
	v_sub_f32_e32 v96, v209, v99
	v_exp_f32_e32 v144, v128
	v_exp_f32_e32 v183, v96
	v_mfma_f32_16x16x32_bf16 v[96:99], v[140:143], v[136:139], v[124:127]
	v_cvt_pk_bf16_f32 v128, v85, v87
	v_cvt_pk_bf16_f32 v130, v86, v130
	v_add_u32_e32 v85, 0x800, v177
	v_cvt_pk_bf16_f32 v124, v211, v153
	v_cvt_pk_bf16_f32 v125, v154, v155
	v_cvt_pk_bf16_f32 v126, v194, v195
	v_cvt_pk_bf16_f32 v127, v193, v196
	s_waitcnt lgkmcnt(0)
	v_mfma_f32_16x16x32_bf16 v[116:119], v[132:135], v[128:131], v[116:119]
	v_add_u32_e32 v97, 0x1000, v177
	v_add_u32_e32 v136, 0x1800, v177
	v_mfma_f32_16x16x32_bf16 v[120:123], v[132:135], v[124:127], v[120:123]
	ds_read2_b64 v[132:135], v85 offset0:32 offset1:36
	s_waitcnt lgkmcnt(0)
; __device__ __forceinline__ float fexp2(float x) { return __builtin_amdgcn_exp2f(x); }
; __device__ __forceinline__ float flog2(float x) { return __builtin_amdgcn_logf(x); }
; template <int MODE>
; __device__ __forceinline__ void sb_step(const char* Kb, const char* Vb, const bf16x8 (&qf)[2][2], const SbConst& U,
;                                         f32x4 (&oacc)[4][2], float (&carry)[2], int key0, int q0, int fr, int fq) {
;     ...
; #pragma unroll
;   for (int ks = 0; ks < 2; ++ks)
; #pragma unroll
;     for (int m = 0; m < 4; ++m) {
;       if (SB_CLS(m, 0) > 0 && SB_CLS(m, 1) > 0) continue;
;       const bf16x8 kf = *(const bf16x8*)(Kb + (m * 16 + fr) * 144 + ks * 64 + fq * 16);
; #pragma unroll
;       for (int n = 0; n < 2; ++n)
;         if (SB_CLS(m, n) <= 0) s[m][n] = mfma16(kf, qf[n][ks], s[m][n]);
;     }
; #pragma unroll
;   for (int n = 0; n < 2; ++n) {
;     unsigned pk[8];
;     const int tq = q0 + n * 16 + fr;
; #pragma unroll
;     for (int m = 0; m < 4; ++m) {
;       if (SB_CLS(m, n) > 0) { pk[m * 2] = 0u; pk[m * 2 + 1] = 0u; continue; }
;       float spv[4];
; #pragma unroll
;       for (int r = 0; r < 4; ++r) {
;         const float z = fminf(s[m][n][r], 80.f);
;         const float e = fexp2(z);
;         float sp = flog2(1.0f + e);
;         float ls = z - sp;
;         if (SB_CLS(m, n) == 0) {
;           const int key = key0 + m * 16 + fq * 4 + r;
;           if (key >= tq) { sp = 0.f; ls = -1e30f; }
;         }
;         spv[r] = sp;
;         s[m][n][r] = ls;
;       }
;       pk[m * 2] = pack2(spv[0], spv[1]);
;       pk[m * 2 + 1] = pack2(spv[2], spv[3]);
;     }
;     ...
; #pragma unroll
;   for (int ks = 0; ks < 2; ++ks) {
;     bf16x8 pf[2];
; #pragma unroll
;     for (int n = 0; n < 2; ++n)
;       pf[n] = mk8(pack2(s[2 * ks][n][0], s[2 * ks][n][1]), pack2(s[2 * ks][n][2], s[2 * ks][n][3]),
;                   pack2(s[2 * ks + 1][n][0], s[2 * ks + 1][n][1]), pack2(s[2 * ks + 1][n][2], s[2 * ks + 1][n][3]));
; #pragma unroll
;     for (int mt = 0; mt < 4; ++mt) {
;       const char* vp = Vb + (mt * 16 + fr) * 144 + (32 * ks + 4 * fq) * 2;
;       const u32x2 lo = *(const u32x2*)vp;
;       const u32x2 hi = *(const u32x2*)(vp + 32);
;       const bf16x8 vf = mk8(lo[0], lo[1], hi[0], hi[1]);
; #pragma unroll
;       for (int n = 0; n < 2; ++n) oacc[mt][n] = mfma16(vf, pf[n], oacc[mt][n]);
;     }
	v_mfma_f32_16x16x32_bf16 v[112:115], v[132:135], v[124:127], v[112:115]
	v_mfma_f32_16x16x32_bf16 v[108:111], v[132:135], v[128:131], v[108:111]
	ds_read2_b64 v[132:135], v97 offset0:64 offset1:68
	s_waitcnt lgkmcnt(0)
	v_mfma_f32_16x16x32_bf16 v[104:107], v[132:135], v[124:127], v[104:107]
	v_mfma_f32_16x16x32_bf16 v[98:101], v[132:135], v[128:131], v[100:103]
	ds_read2_b64 v[132:135], v136 offset0:96 offset1:100
	s_waitcnt lgkmcnt(0)
	v_mfma_f32_16x16x32_bf16 v[92:95], v[132:135], v[124:127], v[92:95]
	v_cvt_pk_bf16_f32 v124, v0, v3
	v_cvt_pk_bf16_f32 v125, v149, v151
	v_cvt_pk_bf16_f32 v126, v1, v148
	v_mfma_f32_16x16x32_bf16 v[86:89], v[132:135], v[128:131], v[88:91]
	ds_read2_b64 v[132:135], v177 offset0:8 offset1:12
	v_cvt_pk_bf16_f32 v127, v150, v152
	v_cvt_pk_bf16_f32 v128, v144, v145
	v_cvt_pk_bf16_f32 v129, v146, v147
	v_cvt_pk_bf16_f32 v130, v180, v181
	v_cvt_pk_bf16_f32 v131, v182, v183
	s_waitcnt lgkmcnt(0)
	v_mfma_f32_16x16x32_bf16 v[120:123], v[132:135], v[124:127], v[120:123]
	v_mfma_f32_16x16x32_bf16 v[116:119], v[132:135], v[128:131], v[116:119]
	ds_read2_b64 v[132:135], v85 offset0:40 offset1:44
	s_waitcnt lgkmcnt(0)
	v_mfma_f32_16x16x32_bf16 v[112:115], v[132:135], v[124:127], v[112:115]
	v_mfma_f32_16x16x32_bf16 v[108:111], v[132:135], v[128:131], v[108:111]
	ds_read2_b64 v[132:135], v97 offset0:72 offset1:76
	s_waitcnt lgkmcnt(0)
	v_mfma_f32_16x16x32_bf16 v[104:107], v[132:135], v[124:127], v[104:107]
	v_mfma_f32_16x16x32_bf16 v[100:103], v[132:135], v[128:131], v[98:101]
	ds_read2_b64 v[132:135], v136 offset0:104 offset1:108
	s_waitcnt lgkmcnt(0)
	v_mfma_f32_16x16x32_bf16 v[92:95], v[132:135], v[124:127], v[92:95]
	v_mfma_f32_16x16x32_bf16 v[88:91], v[132:135], v[128:131], v[86:89]
.LBB0_397:
	s_andn2_saveexec_b64 s[72:73], s[10:11]
	s_cbranch_execz .LBB0_399
	ds_read_b128 v[144:147], v159 offset:64
	ds_read_b128 v[180:183], v159 offset:4672
	s_waitcnt lgkmcnt(5)
	v_mfma_f32_16x16x32_bf16 v[140:143], v[136:139], v[68:71], 0
	s_mov_b32 s58, s56
	s_mov_b32 s59, s56
	s_mov_b32 s57, s56
	v_mfma_f32_16x16x32_bf16 v[136:139], v[136:139], v[76:79], 0
	v_mov_b32_e32 v86, v84
	v_mov_b32_e32 v87, v84
	v_mov_b32_e32 v99, v96
	s_waitcnt lgkmcnt(1)
	v_mfma_f32_16x16x32_bf16 v[140:143], v[144:147], v[72:75], v[140:143]
	v_mfma_f32_16x16x32_bf16 v[144:147], v[144:147], v[80:83], v[136:139]
	s_nop 2
	ds_read_b128 v[136:139], v159 offset:2368
	v_mfma_f32_16x16x32_bf16 v[148:151], v[132:135], v[68:71], 0
	s_nop 2
	v_min_f32_e32 v221, 0x42a00000, v147
	v_exp_f32_e32 v97, v221
	v_mfma_f32_16x16x32_bf16 v[132:135], v[132:135], v[76:79], 0
	v_add_f32_e32 v97, 1.0, v97
	s_waitcnt lgkmcnt(0)
	v_mfma_f32_16x16x32_bf16 v[132:135], v[136:139], v[80:83], v[132:135]
	v_log_f32_e32 v222, v97
	v_mfma_f32_16x16x32_bf16 v[152:155], v[128:131], v[68:71], 0
	v_mfma_f32_16x16x32_bf16 v[128:131], v[128:131], v[76:79], 0
	s_nop 4
	v_min_f32_e32 v223, 0x42a00000, v132
	v_exp_f32_e32 v97, v223
	v_mfma_f32_16x16x32_bf16 v[128:131], v[180:183], v[80:83], v[128:131]
	v_add_f32_e32 v97, 1.0, v97
	v_log_f32_e32 v224, v97
	v_min_f32_e32 v225, 0x42a00000, v133
	v_exp_f32_e32 v97, v225
	v_mfma_f32_16x16x32_bf16 v[148:151], v[136:139], v[72:75], v[148:151]
	v_add_f32_e32 v97, 1.0, v97
	v_log_f32_e32 v226, v97
	v_min_f32_e32 v227, 0x42a00000, v134
	v_exp_f32_e32 v97, v227
	v_mfma_f32_16x16x32_bf16 v[136:139], v[180:183], v[72:75], v[152:155]
	v_min_f32_e32 v180, 0x42a00000, v140
	v_exp_f32_e32 v0, v180
	v_add_f32_e32 v97, 1.0, v97
	v_log_f32_e32 v228, v97
	v_min_f32_e32 v229, 0x42a00000, v135
	v_exp_f32_e32 v97, v229
	v_add_f32_e32 v0, 1.0, v0
	v_log_f32_e32 v181, v0
	v_add_f32_e32 v97, 1.0, v97
	v_log_f32_e32 v230, v97
	v_min_f32_e32 v231, 0x42a00000, v128
	v_exp_f32_e32 v97, v231
	v_min_f32_e32 v193, 0x42a00000, v141
	v_exp_f32_e32 v0, v193
	ds_read_b128 v[152:155], v159 offset:6976
	v_add_f32_e32 v97, 1.0, v97
	v_log_f32_e32 v232, v97
	v_min_f32_e32 v233, 0x42a00000, v129
	v_exp_f32_e32 v97, v233
	v_add_f32_e32 v0, 1.0, v0
	v_log_f32_e32 v194, v0
	v_min_f32_e32 v195, 0x42a00000, v142
	v_add_f32_e32 v97, 1.0, v97
	v_exp_f32_e32 v0, v195
	v_log_f32_e32 v234, v97
	v_min_f32_e32 v235, 0x42a00000, v130
	v_exp_f32_e32 v97, v235
	v_add_f32_e32 v0, 1.0, v0
	v_log_f32_e32 v196, v0
	v_mfma_f32_16x16x32_bf16 v[124:127], v[124:127], v[76:79], 0
	v_min_f32_e32 v197, 0x42a00000, v143
	v_add_f32_e32 v97, 1.0, v97
	v_exp_f32_e32 v0, v197
	v_log_f32_e32 v236, v97
	v_min_f32_e32 v237, 0x42a00000, v131
	v_exp_f32_e32 v97, v237
	s_waitcnt lgkmcnt(0)
; __device__ __forceinline__ float fexp2(float x) { return __builtin_amdgcn_exp2f(x); }
; __device__ __forceinline__ float flog2(float x) { return __builtin_amdgcn_logf(x); }
; template <int MODE>
; __device__ __forceinline__ void sb_step(const char* Kb, const char* Vb, const bf16x8 (&qf)[2][2], const SbConst& U,
;                                         f32x4 (&oacc)[4][2], float (&carry)[2], int key0, int q0, int fr, int fq) {
;     ...
; #pragma unroll
;   for (int n = 0; n < 2; ++n) {
;     unsigned pk[8];
;     const int tq = q0 + n * 16 + fr;
; #pragma unroll
;     for (int m = 0; m < 4; ++m) {
;       if (SB_CLS(m, n) > 0) { pk[m * 2] = 0u; pk[m * 2 + 1] = 0u; continue; }
;       float spv[4];
; #pragma unroll
;       for (int r = 0; r < 4; ++r) {
;         const float z = fminf(s[m][n][r], 80.f);
;         const float e = fexp2(z);
;         float sp = flog2(1.0f + e);
;         float ls = z - sp;
;         if (SB_CLS(m, n) == 0) {
;           const int key = key0 + m * 16 + fq * 4 + r;
;           if (key >= tq) { sp = 0.f; ls = -1e30f; }
;         }
;         spv[r] = sp;
;         s[m][n][r] = ls;
;       }
;       pk[m * 2] = pack2(spv[0], spv[1]);
;       pk[m * 2 + 1] = pack2(spv[2], spv[3]);
;     }
;     const bf16x8 sp0 = mk8(pk[0], pk[1], pk[2], pk[3]);
;     const bf16x8 sp1 = mk8(pk[4], pk[5], pk[6], pk[7]);
;     const float c = carry[n];
;     const f32x4 cin = {c, c, c, c};
;     const f32x4 X1 = mfma16(U.U_ONES, sp1, cin);
;     const f32x4 I0 = mfma16(U.U_TRI1, sp0, X1);
;     const f32x4 I1 = mfma16(U.U_0TRI, sp0, X1);
;     const f32x4 TOT = mfma16(U.U_ONES, sp0, X1);
;     const f32x4 I2 = mfma16(U.U_TRI1, sp1, cin);
;     const f32x4 I3 = mfma16(U.U_0TRI, sp1, cin);
; #pragma unroll
;     for (int r = 0; r < 4; ++r) {
;       s[0][n][r] = (SB_CLS(0, n) > 0) ? 0.f : fexp2(s[0][n][r] - I0[r]);
;       s[1][n][r] = (SB_CLS(1, n) > 0) ? 0.f : fexp2(s[1][n][r] - I1[r]);
;       s[2][n][r] = (SB_CLS(2, n) > 0) ? 0.f : fexp2(s[2][n][r] - I2[r]);
;       s[3][n][r] = (SB_CLS(3, n) > 0) ? 0.f : fexp2(s[3][n][r] - I3[r]);
;     }
;     carry[n] = TOT[0];
	v_mfma_f32_16x16x32_bf16 v[124:127], v[152:155], v[80:83], v[124:127]
	v_add_f32_e32 v0, 1.0, v0
	v_log_f32_e32 v198, v0
	v_max_f32_e32 v0, v148, v148
	v_min_f32_e32 v199, 0x42a00000, v0
	v_add_f32_e32 v97, 1.0, v97
	v_exp_f32_e32 v0, v199
	v_log_f32_e32 v238, v97
	s_nop 0
	v_min_f32_e32 v239, 0x42a00000, v124
	v_exp_f32_e32 v97, v239
	v_add_f32_e32 v0, 1.0, v0
	v_log_f32_e32 v200, v0
	v_min_f32_e32 v201, 0x42a00000, v149
	v_add_f32_e32 v97, 1.0, v97
	v_exp_f32_e32 v0, v201
	v_log_f32_e32 v240, v97
	v_min_f32_e32 v241, 0x42a00000, v125
	v_exp_f32_e32 v97, v241
	v_add_f32_e32 v0, 1.0, v0
	v_min_f32_e32 v182, 0x42a00000, v136
	v_log_f32_e32 v202, v0
	v_exp_f32_e32 v1, v182
	v_min_f32_e32 v203, 0x42a00000, v150
	v_add_f32_e32 v97, 1.0, v97
	v_exp_f32_e32 v0, v203
	v_log_f32_e32 v242, v97
	v_min_f32_e32 v243, 0x42a00000, v126
	v_add_f32_e32 v1, 1.0, v1
	v_exp_f32_e32 v97, v243
	v_log_f32_e32 v183, v1
	v_add_f32_e32 v0, 1.0, v0
	v_min_f32_e32 v207, 0x42a00000, v137
	v_min_f32_e32 v217, 0x42a00000, v138
	v_min_f32_e32 v219, 0x42a00000, v139
	v_log_f32_e32 v204, v0
	v_exp_f32_e32 v1, v207
	v_exp_f32_e32 v3, v217
	v_exp_f32_e32 v85, v219
	v_min_f32_e32 v205, 0x42a00000, v151
	v_add_f32_e32 v97, 1.0, v97
	v_exp_f32_e32 v0, v205
	v_log_f32_e32 v244, v97
	v_min_f32_e32 v245, 0x42a00000, v127
	v_add_f32_e32 v1, 1.0, v1
	v_add_f32_e32 v3, 1.0, v3
	v_add_f32_e32 v85, 1.0, v85
	v_exp_f32_e32 v97, v245
	v_log_f32_e32 v216, v1
	v_log_f32_e32 v218, v3
	v_log_f32_e32 v220, v85
	v_mov_b64_e32 v[138:139], s[58:59]
	v_add_f32_e32 v0, 1.0, v0
	v_mov_b64_e32 v[136:137], s[56:57]
	v_log_f32_e32 v206, v0
	v_add_u32_e32 v0, 0xe0, v158
	v_add_u32_e32 v1, 0xe1, v158
	v_add_u32_e32 v3, 0xe2, v158
	v_add_u32_e32 v85, 0xe3, v158
	v_cmp_lt_i32_e64 s[10:11], v0, v157
	v_cmp_lt_i32_e64 s[12:13], v1, v157
	v_cmp_lt_i32_e64 s[14:15], v3, v157
	v_cmp_lt_i32_e64 s[16:17], v85, v157
	v_add_f32_e32 v97, 1.0, v97
	v_cndmask_b32_e64 v0, 0, v183, s[10:11]
	v_cndmask_b32_e64 v1, 0, v216, s[12:13]
	v_cndmask_b32_e64 v3, 0, v218, s[14:15]
	v_cndmask_b32_e64 v85, 0, v220, s[16:17]
	v_log_f32_e32 v246, v97
	v_cvt_pk_bf16_f32 v0, v0, v1
	v_cvt_pk_bf16_f32 v1, v3, v85
	v_mov_b32_e32 v85, v84
	v_mov_b32_e32 v3, v2
	v_cndmask_b32_e64 v97, 0, v240, s[10:11]
	v_cndmask_b32_e64 v98, 0, v242, s[12:13]
	v_mfma_f32_16x16x32_bf16 v[212:215], v[136:139], v[0:3], v[84:87]
	v_cvt_pk_bf16_f32 v130, v97, v98
	v_cndmask_b32_e64 v97, 0, v244, s[14:15]
	v_cndmask_b32_e64 v98, 0, v246, s[16:17]
	v_cvt_pk_bf16_f32 v208, v181, v194
	v_cvt_pk_bf16_f32 v209, v196, v198
	v_cvt_pk_bf16_f32 v210, v200, v202
	v_cvt_pk_bf16_f32 v211, v204, v206
	v_cvt_pk_bf16_f32 v128, v232, v234
	v_cvt_pk_bf16_f32 v129, v236, v238
	v_cvt_pk_bf16_f32 v131, v97, v98
	v_mov_b32_e32 v97, v96
	v_mov_b32_e32 v98, v96
	v_mfma_f32_16x16x32_bf16 v[140:143], v[4:7], v[208:211], v[212:215]
	v_cvt_pk_bf16_f32 v147, v228, v230
	v_mfma_f32_16x16x32_bf16 v[148:151], v[64:67], v[208:211], v[212:215]
	v_mfma_f32_16x16x32_bf16 v[152:155], v[4:7], v[0:3], v[84:87]
	v_min_f32_e32 v0, 0x42a00000, v144
	v_mfma_f32_16x16x32_bf16 v[84:87], v[136:139], v[208:211], v[212:215]
	v_min_f32_e32 v3, 0x42a00000, v145
	v_exp_f32_e32 v1, v0
	v_mfma_f32_16x16x32_bf16 v[124:127], v[136:139], v[128:131], v[96:99]
	v_add_f32_e32 v1, 1.0, v1
	s_nop 3
	v_mfma_f32_16x16x32_bf16 v[212:215], v[4:7], v[128:131], v[96:99]
	v_min_f32_e32 v86, 0x42a00000, v146
	v_exp_f32_e32 v85, v3
	v_exp_f32_e32 v87, v86
	v_mfma_f32_16x16x32_bf16 v[96:99], v[64:67], v[128:131], v[96:99]
	v_sub_f32_e32 v128, v245, v246
	v_cndmask_b32_e64 v128, v184, v128, s[16:17]
	v_add_f32_e32 v85, 1.0, v85
	v_add_f32_e32 v87, 1.0, v87
	v_log_f32_e32 v1, v1
	s_nop 2
	v_sub_f32_e32 v99, v128, v99
	v_exp_f32_e32 v245, v99
	v_sub_f32_e32 v99, v239, v240
	v_cndmask_b32_e64 v99, v184, v99, s[10:11]
	v_sub_f32_e32 v96, v99, v96
	v_exp_f32_e32 v239, v96
	v_sub_f32_e32 v96, v241, v242
	v_cndmask_b32_e64 v96, v184, v96, s[12:13]
	v_sub_f32_e32 v96, v96, v97
	v_exp_f32_e32 v240, v96
	v_sub_f32_e32 v96, v243, v244
	v_cndmask_b32_e64 v96, v184, v96, s[14:15]
	v_sub_f32_e32 v96, v96, v98
	v_log_f32_e32 v85, v85
	v_log_f32_e32 v87, v87
	v_exp_f32_e32 v241, v96
	v_sub_f32_e32 v96, v237, v238
	v_sub_f32_e32 v96, v96, v215
	v_exp_f32_e32 v215, v96
	v_sub_f32_e32 v96, v231, v232
	v_sub_f32_e32 v96, v96, v212
	v_cvt_pk_bf16_f32 v144, v1, v85
	v_cvt_pk_bf16_f32 v145, v87, v222
	v_cvt_pk_bf16_f32 v146, v224, v226
	v_exp_f32_e32 v212, v96
	v_sub_f32_e32 v96, v233, v234
	v_mfma_f32_16x16x32_bf16 v[208:211], v[64:67], v[144:147], v[124:127]
	v_sub_f32_e32 v96, v96, v213
	v_exp_f32_e32 v213, v96
	v_sub_f32_e32 v96, v235, v236
	v_sub_f32_e32 v96, v96, v214
	v_exp_f32_e32 v214, v96
	v_sub_f32_e32 v96, v229, v230
	s_nop 1
	v_sub_f32_e32 v96, v96, v211
	v_exp_f32_e32 v131, v96
	v_sub_f32_e32 v96, v223, v224
	v_sub_f32_e32 v96, v96, v208
	v_exp_f32_e32 v130, v96
	v_sub_f32_e32 v96, v225, v226
	v_mfma_f32_16x16x32_bf16 v[132:135], v[4:7], v[144:147], v[124:127]
	v_sub_f32_e32 v96, v96, v209
	v_exp_f32_e32 v208, v96
	v_sub_f32_e32 v96, v227, v228
	v_sub_f32_e32 v96, v96, v210
	v_exp_f32_e32 v209, v96
	v_sub_f32_e32 v96, v221, v222
	s_nop 1
	v_sub_f32_e32 v96, v96, v135
	v_exp_f32_e32 v129, v96
	v_sub_f32_e32 v96, v201, v202
	v_sub_f32_e32 v0, v0, v1
	v_sub_f32_e32 v1, v3, v85
	v_sub_f32_e32 v3, v86, v87
	v_sub_f32_e32 v86, v182, v183
	v_sub_f32_e32 v96, v96, v149
	v_cndmask_b32_e64 v86, v184, v86, s[10:11]
	v_exp_f32_e32 v128, v96
	v_sub_f32_e32 v96, v203, v204
	v_sub_f32_e32 v86, v86, v152
	v_sub_f32_e32 v96, v96, v150
	v_sub_f32_e32 v0, v0, v132
	v_exp_f32_e32 v152, v86
	v_sub_f32_e32 v86, v207, v216
	v_exp_f32_e32 v132, v96
	v_sub_f32_e32 v96, v197, v198
	v_cndmask_b32_e64 v86, v184, v86, s[12:13]
	v_sub_f32_e32 v96, v96, v143
	v_sub_f32_e32 v1, v1, v133
	v_sub_f32_e32 v86, v86, v153
	v_exp_f32_e32 v133, v96
	v_sub_f32_e32 v96, v180, v181
	v_exp_f32_e32 v153, v86
	v_sub_f32_e32 v86, v217, v218
	v_sub_f32_e32 v96, v96, v140
	v_sub_f32_e32 v3, v3, v134
	v_cndmask_b32_e64 v86, v184, v86, s[14:15]
	v_exp_f32_e32 v134, v96
	v_sub_f32_e32 v96, v193, v194
	v_sub_f32_e32 v86, v86, v154
	v_sub_f32_e32 v96, v96, v141
	v_exp_f32_e32 v154, v86
	v_sub_f32_e32 v86, v205, v206
	v_exp_f32_e32 v135, v96
	v_sub_f32_e32 v96, v195, v196
	v_sub_f32_e32 v86, v86, v151
	v_sub_f32_e32 v96, v96, v142
	v_exp_f32_e32 v86, v86
	v_exp_f32_e32 v140, v96
	v_mfma_f32_16x16x32_bf16 v[96:99], v[136:139], v[144:147], v[124:127]
	v_sub_f32_e32 v87, v199, v200
	v_sub_f32_e32 v87, v87, v148
	v_exp_f32_e32 v0, v0
	v_cvt_pk_bf16_f32 v124, v134, v135
	v_cvt_pk_bf16_f32 v125, v140, v133
	v_cvt_pk_bf16_f32 v127, v132, v86
	ds_read2_b64 v[132:135], v177 offset1:4
	v_exp_f32_e32 v1, v1
	v_exp_f32_e32 v3, v3
	v_exp_f32_e32 v87, v87
	v_cvt_pk_bf16_f32 v130, v130, v208
	v_cvt_pk_bf16_f32 v131, v209, v131
	v_cvt_pk_bf16_f32 v129, v3, v129
	v_cvt_pk_bf16_f32 v126, v87, v128
	v_cvt_pk_bf16_f32 v128, v0, v1
	v_add_u32_e32 v97, 0x800, v177
	s_waitcnt lgkmcnt(0)
; template <int MODE>
; __device__ __forceinline__ void sb_step(const char* Kb, const char* Vb, const bf16x8 (&qf)[2][2], const SbConst& U,
;                                         f32x4 (&oacc)[4][2], float (&carry)[2], int key0, int q0, int fr, int fq) {
;     ...
; #pragma unroll
;   for (int ks = 0; ks < 2; ++ks) {
;     bf16x8 pf[2];
; #pragma unroll
;     for (int n = 0; n < 2; ++n)
;       pf[n] = mk8(pack2(s[2 * ks][n][0], s[2 * ks][n][1]), pack2(s[2 * ks][n][2], s[2 * ks][n][3]),
;                   pack2(s[2 * ks + 1][n][0], s[2 * ks + 1][n][1]), pack2(s[2 * ks + 1][n][2], s[2 * ks + 1][n][3]));
; #pragma unroll
;     for (int mt = 0; mt < 4; ++mt) {
;       const char* vp = Vb + (mt * 16 + fr) * 144 + (32 * ks + 4 * fq) * 2;
;       const u32x2 lo = *(const u32x2*)vp;
;       const u32x2 hi = *(const u32x2*)(vp + 32);
;       const bf16x8 vf = mk8(lo[0], lo[1], hi[0], hi[1]);
; #pragma unroll
;       for (int n = 0; n < 2; ++n) oacc[mt][n] = mfma16(vf, pf[n], oacc[mt][n]);
;     }
	v_mfma_f32_16x16x32_bf16 v[120:123], v[132:135], v[124:127], v[120:123]
	v_add_u32_e32 v136, 0x1000, v177
	v_add_u32_e32 v137, 0x1800, v177
	v_sub_f32_e32 v85, v219, v220
	v_mfma_f32_16x16x32_bf16 v[116:119], v[132:135], v[128:131], v[116:119]
	ds_read2_b64 v[132:135], v97 offset0:32 offset1:36
	v_cndmask_b32_e64 v85, v184, v85, s[16:17]
	v_sub_f32_e32 v85, v85, v155
	s_waitcnt lgkmcnt(0)
	v_mfma_f32_16x16x32_bf16 v[112:115], v[132:135], v[124:127], v[112:115]
	v_exp_f32_e32 v85, v85
	v_cvt_pk_bf16_f32 v0, v152, v153
	v_mov_b32_e32 v3, v2
	v_mfma_f32_16x16x32_bf16 v[108:111], v[132:135], v[128:131], v[108:111]
	ds_read2_b64 v[132:135], v136 offset0:64 offset1:68
	v_cvt_pk_bf16_f32 v1, v154, v85
	s_waitcnt lgkmcnt(0)
	v_mfma_f32_16x16x32_bf16 v[104:107], v[132:135], v[124:127], v[104:107]
	v_mfma_f32_16x16x32_bf16 v[98:101], v[132:135], v[128:131], v[100:103]
	ds_read2_b64 v[132:135], v137 offset0:96 offset1:100
	s_waitcnt lgkmcnt(0)
	v_mfma_f32_16x16x32_bf16 v[86:89], v[132:135], v[128:131], v[88:91]
	ds_read2_b64 v[128:131], v177 offset0:8 offset1:12
	v_mfma_f32_16x16x32_bf16 v[92:95], v[132:135], v[124:127], v[92:95]
	v_cvt_pk_bf16_f32 v124, v212, v213
	v_cvt_pk_bf16_f32 v125, v214, v215
	v_cvt_pk_bf16_f32 v126, v239, v240
	v_cvt_pk_bf16_f32 v127, v241, v245
	s_waitcnt lgkmcnt(0)
	v_mfma_f32_16x16x32_bf16 v[120:123], v[128:131], v[0:3], v[120:123]
	v_mfma_f32_16x16x32_bf16 v[116:119], v[128:131], v[124:127], v[116:119]
	ds_read2_b64 v[128:131], v97 offset0:40 offset1:44
	s_waitcnt lgkmcnt(0)
	v_mfma_f32_16x16x32_bf16 v[112:115], v[128:131], v[0:3], v[112:115]
	v_mfma_f32_16x16x32_bf16 v[108:111], v[128:131], v[124:127], v[108:111]
	ds_read2_b64 v[128:131], v136 offset0:72 offset1:76
	s_waitcnt lgkmcnt(0)
	v_mfma_f32_16x16x32_bf16 v[104:107], v[128:131], v[0:3], v[104:107]
	v_mfma_f32_16x16x32_bf16 v[100:103], v[128:131], v[124:127], v[98:101]
	ds_read2_b64 v[128:131], v137 offset0:104 offset1:108
	s_waitcnt lgkmcnt(0)
	v_mfma_f32_16x16x32_bf16 v[92:95], v[128:131], v[0:3], v[92:95]
	v_mfma_f32_16x16x32_bf16 v[88:91], v[128:131], v[124:127], v[86:89]

; __device__ __forceinline__ void sb_phase(const Params& p, char* shm, int wv, int vb) {
;     ...
;         if (key0 == q0) sb_step<1>(Kb, Vb, qf, U, oacc, carry, key0, q0, fr, fq);
;         else if (key0 + 32 == q0) sb_step<2>(Kb, Vb, qf, U, oacc, carry, key0, q0, fr, fq);
;         else sb_step<0>(Kb, Vb, qf, U, oacc, carry, key0, q0, fr, fq);
.LBB0_400:
	s_andn2_saveexec_b64 s[10:11], s[54:55]
	s_cbranch_execz .LBB0_391
; template <int MODE>
; __device__ __forceinline__ void sb_step(const char* Kb, const char* Vb, const bf16x8 (&qf)[2][2], const SbConst& U,
;                                         f32x4 (&oacc)[4][2], float (&carry)[2], int key0, int q0, int fr, int fq) {
;     ...
; #pragma unroll
;   for (int ks = 0; ks < 2; ++ks)
; #pragma unroll
;     for (int m = 0; m < 4; ++m) {
;       if (SB_CLS(m, 0) > 0 && SB_CLS(m, 1) > 0) continue;
;       const bf16x8 kf = *(const bf16x8*)(Kb + (m * 16 + fr) * 144 + ks * 64 + fq * 16);
; #pragma unroll
;       for (int n = 0; n < 2; ++n)
;         if (SB_CLS(m, n) <= 0) s[m][n] = mfma16(kf, qf[n][ks], s[m][n]);
;     }
; #pragma unroll
;   for (int n = 0; n < 2; ++n) {
;     unsigned pk[8];
;     const int tq = q0 + n * 16 + fr;
; #pragma unroll
;     for (int m = 0; m < 4; ++m) {
;       if (SB_CLS(m, n) > 0) { pk[m * 2] = 0u; pk[m * 2 + 1] = 0u; continue; }
;       float spv[4];
; #pragma unroll
;       for (int r = 0; r < 4; ++r) {
;         const float z = fminf(s[m][n][r], 80.f);
;         const float e = fexp2(z);
;         float sp = flog2(1.0f + e);
;         float ls = z - sp;
;         if (SB_CLS(m, n) == 0) {
;           const int key = key0 + m * 16 + fq * 4 + r;
;           if (key >= tq) { sp = 0.f; ls = -1e30f; }
;         }
;         spv[r] = sp;
;         s[m][n][r] = ls;
;       }
;       pk[m * 2] = pack2(spv[0], spv[1]);
;       pk[m * 2 + 1] = pack2(spv[2], spv[3]);
;     }
;     const bf16x8 sp0 = mk8(pk[0], pk[1], pk[2], pk[3]);
;     const bf16x8 sp1 = mk8(pk[4], pk[5], pk[6], pk[7]);
;     const float c = carry[n];
;     const f32x4 cin = {c, c, c, c};
;     const f32x4 X1 = mfma16(U.U_ONES, sp1, cin);
;     const f32x4 I0 = mfma16(U.U_TRI1, sp0, X1);
;     const f32x4 I1 = mfma16(U.U_0TRI, sp0, X1);
;     const f32x4 TOT = mfma16(U.U_ONES, sp0, X1);
;     const f32x4 I2 = mfma16(U.U_TRI1, sp1, cin);
;     const f32x4 I3 = mfma16(U.U_0TRI, sp1, cin);
; #pragma unroll
;     for (int r = 0; r < 4; ++r) {
;       s[0][n][r] = (SB_CLS(0, n) > 0) ? 0.f : fexp2(s[0][n][r] - I0[r]);
;       s[1][n][r] = (SB_CLS(1, n) > 0) ? 0.f : fexp2(s[1][n][r] - I1[r]);
;       s[2][n][r] = (SB_CLS(2, n) > 0) ? 0.f : fexp2(s[2][n][r] - I2[r]);
;       s[3][n][r] = (SB_CLS(3, n) > 0) ? 0.f : fexp2(s[3][n][r] - I3[r]);
;     }
;     carry[n] = TOT[0];
;     ...
; #pragma unroll
;   for (int ks = 0; ks < 2; ++ks) {
;     bf16x8 pf[2];
	s_waitcnt lgkmcnt(1)
	ds_read_b128 v[128:131], v159
	ds_read_b128 v[140:143], v159 offset:64
	ds_read_b128 v[136:139], v159 offset:2304
	s_mov_b32 s58, s56
	s_mov_b32 s59, s56
	s_mov_b32 s57, s56
	s_mov_b32 s54, s52
	s_mov_b32 s55, s52
	s_mov_b32 s53, s52
	s_waitcnt lgkmcnt(2)
	v_mfma_f32_16x16x32_bf16 v[132:135], v[128:131], v[68:71], 0
	v_mov_b64_e32 v[126:127], s[54:55]
	v_mov_b64_e32 v[124:125], s[52:53]
	v_mov_b32_e32 v86, v84
	v_mfma_f32_16x16x32_bf16 v[128:131], v[128:131], v[76:79], 0
	v_mov_b32_e32 v87, v84
	s_waitcnt lgkmcnt(1)
	v_mfma_f32_16x16x32_bf16 v[132:135], v[140:143], v[72:75], v[132:135]
	v_mfma_f32_16x16x32_bf16 v[140:143], v[140:143], v[80:83], v[128:131]
	s_nop 3
	ds_read_b128 v[128:131], v159 offset:2368
	s_nop 1
	v_min_f32_e32 v148, 0x42a00000, v132
	v_min_f32_e32 v150, 0x42a00000, v133
	v_min_f32_e32 v152, 0x42a00000, v134
	v_min_f32_e32 v154, 0x42a00000, v135
	v_exp_f32_e32 v0, v148
	v_exp_f32_e32 v1, v150
	v_exp_f32_e32 v3, v152
	v_exp_f32_e32 v85, v154
	s_waitcnt lgkmcnt(1)
	v_mfma_f32_16x16x32_bf16 v[136:139], v[136:139], v[76:79], 0
	v_add_f32_e32 v0, 1.0, v0
	v_add_f32_e32 v1, 1.0, v1
	v_add_f32_e32 v3, 1.0, v3
	v_add_f32_e32 v85, 1.0, v85
	v_log_f32_e32 v149, v0
	v_log_f32_e32 v151, v1
	v_log_f32_e32 v153, v3
	v_log_f32_e32 v155, v85
	v_mov_b64_e32 v[134:135], s[58:59]
	v_min_f32_e32 v180, 0x42a00000, v143
	v_mov_b64_e32 v[132:133], s[56:57]
	v_exp_f32_e32 v97, v180
	s_waitcnt lgkmcnt(0)
	v_mfma_f32_16x16x32_bf16 v[128:131], v[128:131], v[80:83], v[136:139]
	v_cndmask_b32_e64 v0, 0, v149, s[2:3]
	v_cndmask_b32_e32 v1, 0, v151, vcc
	v_cndmask_b32_e64 v3, 0, v153, s[6:7]
	v_cndmask_b32_e64 v85, 0, v155, s[8:9]
	v_cvt_pk_bf16_f32 v0, v0, v1
	v_cvt_pk_bf16_f32 v1, v3, v85
	v_mov_b32_e32 v85, v84
	v_add_f32_e32 v97, 1.0, v97
	v_log_f32_e32 v181, v97
	v_mfma_f32_16x16x32_bf16 v[84:87], v[132:135], v[124:127], v[84:87]
	v_max_f32_e32 v97, v128, v128
	v_min_f32_e32 v182, 0x42a00000, v97
	v_min_f32_e32 v193, 0x42a00000, v129
	v_min_f32_e32 v195, 0x42a00000, v130
	v_min_f32_e32 v197, 0x42a00000, v131
	v_exp_f32_e32 v97, v182
	v_exp_f32_e32 v98, v193
	v_exp_f32_e32 v99, v195
	v_exp_f32_e32 v128, v197
	v_mov_b32_e32 v3, v2
	v_add_f32_e32 v97, 1.0, v97
	v_add_f32_e32 v98, 1.0, v98
	v_mfma_f32_16x16x32_bf16 v[136:139], v[4:7], v[0:3], v[84:87]
	v_add_f32_e32 v99, 1.0, v99
	v_add_f32_e32 v128, 1.0, v128
	v_log_f32_e32 v183, v97
	v_mfma_f32_16x16x32_bf16 v[84:87], v[132:135], v[0:3], v[84:87]
	v_max_f32_e32 v0, v140, v140
	v_max_f32_e32 v3, v141, v141
	v_min_f32_e32 v0, 0x42a00000, v0
	v_min_f32_e32 v3, 0x42a00000, v3
	v_exp_f32_e32 v1, v0
	s_nop 2
	v_min_f32_e32 v86, 0x42a00000, v142
	v_exp_f32_e32 v85, v3
	v_exp_f32_e32 v87, v86
	v_log_f32_e32 v194, v98
	v_log_f32_e32 v196, v99
	v_log_f32_e32 v198, v128
	v_add_f32_e32 v1, 1.0, v1
	v_add_f32_e32 v85, 1.0, v85
	v_add_f32_e32 v87, 1.0, v87
	v_cndmask_b32_e64 v97, 0, v183, s[2:3]
	v_cndmask_b32_e32 v98, 0, v194, vcc
	v_cndmask_b32_e64 v99, 0, v196, s[6:7]
	v_cndmask_b32_e64 v128, 0, v198, s[8:9]
	v_log_f32_e32 v1, v1
	v_log_f32_e32 v85, v85
	v_log_f32_e32 v87, v87
	v_cvt_pk_bf16_f32 v142, v97, v98
	v_cvt_pk_bf16_f32 v143, v99, v128
	v_mov_b32_e32 v97, v96
	v_mov_b32_e32 v98, v96
	v_mov_b32_e32 v99, v96
	v_cvt_pk_bf16_f32 v140, v1, v85
	v_cvt_pk_bf16_f32 v141, v87, v181
	v_mfma_f32_16x16x32_bf16 v[96:99], v[132:135], v[124:127], v[96:99]
	v_sub_f32_e32 v0, v0, v1
	v_sub_f32_e32 v182, v182, v183
	v_cndmask_b32_e64 v182, v184, v182, s[2:3]
	v_mfma_f32_16x16x32_bf16 v[128:131], v[4:7], v[140:143], v[96:99]
	v_sub_f32_e32 v197, v197, v198
	v_cndmask_b32_e64 v197, v184, v197, s[8:9]
	v_sub_f32_e32 v180, v180, v181
	v_mfma_f32_16x16x32_bf16 v[144:147], v[64:67], v[140:143], v[96:99]
	v_mfma_f32_16x16x32_bf16 v[96:99], v[132:135], v[140:143], v[96:99]
	s_nop 2
	v_sub_f32_e32 v0, v0, v128
	v_exp_f32_e32 v128, v0
	v_sub_f32_e32 v0, v3, v85
	v_sub_f32_e32 v0, v0, v129
	v_exp_f32_e32 v3, v0
	v_sub_f32_e32 v0, v86, v87
	v_sub_f32_e32 v0, v0, v130
	v_exp_f32_e32 v85, v0
	v_sub_f32_e32 v0, v154, v155
	v_sub_f32_e32 v144, v182, v144
	v_sub_f32_e32 v182, v193, v194
	v_cndmask_b32_e64 v0, v184, v0, s[8:9]
	v_cndmask_b32_e32 v182, v184, v182, vcc
	v_sub_f32_e32 v0, v0, v139
	ds_read2_b64 v[132:135], v177 offset1:4
	v_sub_f32_e32 v145, v182, v145
	v_sub_f32_e32 v182, v195, v196
	v_exp_f32_e32 v1, v0
	v_sub_f32_e32 v0, v148, v149
	v_sub_f32_e32 v86, v150, v151
	v_sub_f32_e32 v87, v152, v153
	v_cndmask_b32_e64 v182, v184, v182, s[6:7]
	v_cndmask_b32_e64 v0, v184, v0, s[2:3]
	v_cndmask_b32_e32 v86, v184, v86, vcc
	v_cndmask_b32_e64 v87, v184, v87, s[6:7]
	v_sub_f32_e32 v147, v197, v147
	v_sub_f32_e32 v146, v182, v146
	v_sub_f32_e32 v131, v180, v131
	v_sub_f32_e32 v0, v0, v136
	v_sub_f32_e32 v86, v86, v137
	v_sub_f32_e32 v87, v87, v138
	v_exp_f32_e32 v147, v147
	v_exp_f32_e32 v144, v144
	v_exp_f32_e32 v145, v145
	v_exp_f32_e32 v146, v146
	v_exp_f32_e32 v131, v131
	v_exp_f32_e32 v0, v0
	v_exp_f32_e32 v86, v86
	v_exp_f32_e32 v87, v87
	v_cvt_pk_bf16_f32 v128, v128, v3
	v_cvt_pk_bf16_f32 v129, v85, v131
	v_cvt_pk_bf16_f32 v0, v0, v86
	v_cvt_pk_bf16_f32 v1, v87, v1
	v_cvt_pk_bf16_f32 v130, v144, v145
	v_cvt_pk_bf16_f32 v131, v146, v147
	v_mov_b32_e32 v3, v2
	v_add_u32_e32 v85, 0x800, v177
	s_waitcnt lgkmcnt(0)
	v_mfma_f32_16x16x32_bf16 v[116:119], v[132:135], v[128:131], v[116:119]
	v_add_u32_e32 v97, 0x1000, v177
	v_add_u32_e32 v136, 0x1800, v177
	v_mfma_f32_16x16x32_bf16 v[120:123], v[132:135], v[0:3], v[120:123]
	ds_read2_b64 v[132:135], v85 offset0:32 offset1:36
	s_waitcnt lgkmcnt(0)
	v_mfma_f32_16x16x32_bf16 v[112:115], v[132:135], v[0:3], v[112:115]
	v_mfma_f32_16x16x32_bf16 v[108:111], v[132:135], v[128:131], v[108:111]
	ds_read2_b64 v[132:135], v97 offset0:64 offset1:68
	s_waitcnt lgkmcnt(0)
	v_mfma_f32_16x16x32_bf16 v[104:107], v[132:135], v[0:3], v[104:107]
	v_mfma_f32_16x16x32_bf16 v[98:101], v[132:135], v[128:131], v[100:103]
	ds_read2_b64 v[132:135], v136 offset0:96 offset1:100
	s_waitcnt lgkmcnt(0)
	v_mfma_f32_16x16x32_bf16 v[86:89], v[132:135], v[128:131], v[88:91]
	ds_read2_b64 v[128:131], v177 offset0:8 offset1:12
	s_waitcnt lgkmcnt(0)
	v_mfma_f32_16x16x32_bf16 v[120:123], v[128:131], v[124:127], v[120:123]
	v_mfma_f32_16x16x32_bf16 v[116:119], v[128:131], v[124:127], v[116:119]
	ds_read2_b64 v[128:131], v85 offset0:40 offset1:44
	s_waitcnt lgkmcnt(0)
	v_mfma_f32_16x16x32_bf16 v[112:115], v[128:131], v[124:127], v[112:115]
	v_mfma_f32_16x16x32_bf16 v[108:111], v[128:131], v[124:127], v[108:111]
	ds_read2_b64 v[128:131], v97 offset0:72 offset1:76
	s_waitcnt lgkmcnt(0)
	v_mfma_f32_16x16x32_bf16 v[104:107], v[128:131], v[124:127], v[104:107]
	v_mfma_f32_16x16x32_bf16 v[100:103], v[128:131], v[124:127], v[98:101]
	ds_read2_b64 v[128:131], v136 offset0:104 offset1:108
	v_mfma_f32_16x16x32_bf16 v[92:95], v[132:135], v[0:3], v[92:95]
	s_waitcnt lgkmcnt(0)
	v_mfma_f32_16x16x32_bf16 v[92:95], v[128:131], v[124:127], v[92:95]
	v_mfma_f32_16x16x32_bf16 v[88:91], v[128:131], v[124:127], v[86:89]
	s_branch .LBB0_391
